# XCC-local barriers additionally skip the L2 write-back (producers and consumers share the XCC L2 by construction)
# baseline (speedup 1.0000x reference)
.LBB0_342:
	s_andn2_saveexec_b64 s[0:1], s[0:1]
	s_cbranch_execz .LBB0_362
	s_mov_b64 s[0:1], exec
	s_cmp_eq_u32 s33, 0x100
	s_cbranch_scc1 .LBB0_359
	buffer_wbl2 sc1
	s_waitcnt lgkmcnt(0)
	s_waitcnt vmcnt(0)
	v_mbcnt_lo_u32_b32 v1, s0, 0
	v_mbcnt_hi_u32_b32 v1, s1, v1
	v_cmp_eq_u32_e32 vcc, 0, v1
	s_and_saveexec_b64 s[6:7], vcc
	s_cbranch_execz .LBB0_345
	s_bcnt1_i32_b64 s0, s[0:1]
	v_mov_b32_e32 v2, s0
	v_readlane_b32 s0, v253, 15
	v_readlane_b32 s1, v253, 16
	s_nop 4
	global_atomic_add v2, v177, v2, s[0:1] sc0
